# GEMM mainloop: lgkmcnt(4) before the pre-MFMA barrier in phases 3 and 7 (half of B-fragment reads landed before barrier)
# baseline (speedup 1.0000x reference)
; #define PG8_STAGE(bufoff, gbase, voff) do { _Pragma("unroll") for (int _i = 0; _i < 2; ++_i) \
;         __builtin_amdgcn_global_load_lds((const unsigned*)((const char*)(gbase) + (voff)[_i]), (LAS unsigned*)(lds + (bufoff) + ldsw + _i * 8192), 16, 0, 0); } while (0)
; #define PG8_LDA(dst, b, h) do { _Pragma("unroll") for (int m = 0; m < 4; ++m) _Pragma("unroll") for (int k = 0; k < 2; ++k) dst[m][k] = *(const LAS f16x8*)(lds + PG8_SA(b, h) + aoff + m * 2048 + k * 1024); } while (0)
; #define PG8_LDB(dst, b, h) do { _Pragma("unroll") for (int n = 0; n < 2; ++n) _Pragma("unroll") for (int k = 0; k < 2; ++k) dst[n][k] = *(const LAS f16x8*)(lds + PG8_SB(b, h) + boff + n * 2048 + k * 1024); } while (0)
; #define PG8_MMA(ai, bj, At, Bt) do { __builtin_amdgcn_s_setprio(1); _Pragma("unroll") for (int m = 0; m < 4; ++m) _Pragma("unroll") for (int n = 0; n < 2; ++n) _Pragma("unroll") for (int k = 0; k < 2; ++k) \
;         acc[ai][bj][m][n] = __builtin_amdgcn_mfma_f32_16x16x32_f16(Bt[n][k], At[m][k], acc[ai][bj][m][n], 0, 0, 0); __builtin_amdgcn_s_setprio(0); } while (0)
; #define PG8_WAIT_L(n) asm volatile("s_waitcnt lgkmcnt(" #n ")" ::: "memory")
; #define PG8_BAR __builtin_amdgcn_s_barrier()
; #define PG8_SCHED __builtin_amdgcn_sched_barrier(0)
; __device__ __forceinline__ void gemm_phase(LAS unsigned char* lds, const Job& g, const pg8::StaticOrder& S) {
;     ...
;             PG8_LDB(B0, 0, 0); PG8_SCHED; PG8_LDA(At, 0, 0); PG8_STAGE(PG8_SA(1, 1), a1 + hA, voffA);
;             PG8_WAIT_L(8); PG8_BAR; PG8_WAIT_L(0); PG8_MMA(0, 0, At, B0); PG8_BAR; PG8_SCHED;
;             PG8_LDB(B1, 0, 1); PG8_STAGE(PG8_SB(0, 0), b2, voffB);
;             PG8_BAR; PG8_WAIT_L(0); PG8_MMA(0, 1, At, B1); PG8_BAR;
;             PG8_LDA(At, 0, 1); PG8_STAGE(PG8_SA(0, 0), a2, voffA);
;             PG8_BAR; PG8_WAIT_L(0); PG8_MMA(1, 0, At, B0); PG8_BAR; PG8_SCHED;
.LBB0_182:
	s_add_i32 s44, s24, 2
	s_add_u32 s45, s10, 0x80
	s_addc_u32 s25, s11, 0
	s_add_i32 s80, 0, 0x10000
	v_add_u32_e32 v148, s80, v238
	s_waitcnt lgkmcnt(0)
	ds_read_b128 v[136:139], v148
	ds_read_b128 v[140:143], v148 offset:1024
	ds_read_b128 v[144:147], v148 offset:2048
	ds_read_b128 v[148:151], v148 offset:3072
	s_cmp_eq_u32 s97, s24
	s_cselect_b32 s24, s22, s45
	s_cselect_b32 s25, s23, s25
	s_cselect_b32 s63, s13, vcc_hi
	s_cselect_b32 s62, s12, vcc_lo
	v_lshl_add_u64 v[204:205], s[10:11], 0, v[200:201]
	s_add_i32 m0, s49, 0xc000
	ds_read_b128 v[152:155], v241
	ds_read_b128 v[156:159], v241 offset:1024
	ds_read_b128 v[160:163], v241 offset:2048
	ds_read_b128 v[164:167], v241 offset:3072
	ds_read_b128 v[168:171], v241 offset:4096
	ds_read_b128 v[172:175], v241 offset:5120
	ds_read_b128 v[176:179], v241 offset:6144
	ds_read_b128 v[180:183], v241 offset:7168
	global_load_lds_dwordx4 v[204:205], off
	v_lshl_add_u64 v[204:205], s[10:11], 0, v[202:203]
	s_add_i32 m0, s49, 0xe000
	s_nop 0
	global_load_lds_dwordx4 v[204:205], off
	s_waitcnt lgkmcnt(8)
	s_barrier
	s_waitcnt lgkmcnt(0)
	v_mfma_f32_16x16x32_f16 v[132:135], v[136:139], v[152:155], v[132:135]
	v_mfma_f32_16x16x32_f16 v[128:131], v[144:147], v[152:155], v[128:131]
	v_mfma_f32_16x16x32_f16 v[116:119], v[136:139], v[160:163], v[116:119]
	v_mfma_f32_16x16x32_f16 v[112:115], v[144:147], v[160:163], v[112:115]
	v_mfma_f32_16x16x32_f16 v[100:103], v[136:139], v[168:171], v[100:103]
	v_mfma_f32_16x16x32_f16 v[96:99], v[144:147], v[168:171], v[96:99]
	v_mfma_f32_16x16x32_f16 v[84:87], v[136:139], v[176:179], v[84:87]
	v_mfma_f32_16x16x32_f16 v[80:83], v[144:147], v[176:179], v[80:83]
	v_mfma_f32_16x16x32_f16 v[132:135], v[140:143], v[156:159], v[132:135]
	v_mfma_f32_16x16x32_f16 v[128:131], v[148:151], v[156:159], v[128:131]
	v_mfma_f32_16x16x32_f16 v[116:119], v[140:143], v[164:167], v[116:119]
	v_mfma_f32_16x16x32_f16 v[112:115], v[148:151], v[164:167], v[112:115]
	v_mfma_f32_16x16x32_f16 v[100:103], v[140:143], v[172:175], v[100:103]
	v_mfma_f32_16x16x32_f16 v[96:99], v[148:151], v[172:175], v[96:99]
	v_mfma_f32_16x16x32_f16 v[84:87], v[140:143], v[180:183], v[84:87]
	v_mfma_f32_16x16x32_f16 v[80:83], v[148:151], v[180:183], v[80:83]
	s_barrier
	s_add_i32 s45, 0, 0x14000
	s_add_i32 s80, s80, s48
	v_add_u32_e32 v216, s45, v238
	v_lshl_add_u64 v[242:243], s[62:63], 0, v[194:195]
	s_mov_b32 m0, s80
	ds_read_b128 v[204:207], v216
	ds_read_b128 v[208:211], v216 offset:1024
	ds_read_b128 v[212:215], v216 offset:2048
	ds_read_b128 v[216:219], v216 offset:3072
	global_load_lds_dwordx4 v[242:243], off
	v_lshl_add_u64 v[244:245], s[62:63], 0, v[198:199]
	s_add_i32 m0, s80, 0x2000
	s_nop 0
	global_load_lds_dwordx4 v[244:245], off
	s_barrier
	s_waitcnt lgkmcnt(0)
	v_mfma_f32_16x16x32_f16 v[124:127], v[204:207], v[152:155], v[124:127]
	v_mfma_f32_16x16x32_f16 v[120:123], v[212:215], v[152:155], v[120:123]
	v_mfma_f32_16x16x32_f16 v[108:111], v[204:207], v[160:163], v[108:111]
	v_mfma_f32_16x16x32_f16 v[104:107], v[212:215], v[160:163], v[104:107]
	v_mfma_f32_16x16x32_f16 v[92:95], v[204:207], v[168:171], v[92:95]
	v_mfma_f32_16x16x32_f16 v[88:91], v[212:215], v[168:171], v[88:91]
	v_mfma_f32_16x16x32_f16 v[76:79], v[204:207], v[176:179], v[76:79]
	v_mfma_f32_16x16x32_f16 v[72:75], v[212:215], v[176:179], v[72:75]
	v_mfma_f32_16x16x32_f16 v[124:127], v[208:211], v[156:159], v[124:127]
	v_mfma_f32_16x16x32_f16 v[120:123], v[216:219], v[156:159], v[120:123]
	v_mfma_f32_16x16x32_f16 v[108:111], v[208:211], v[164:167], v[108:111]
	v_mfma_f32_16x16x32_f16 v[104:107], v[216:219], v[164:167], v[104:107]
	v_mfma_f32_16x16x32_f16 v[92:95], v[208:211], v[172:175], v[92:95]
	v_mfma_f32_16x16x32_f16 v[88:91], v[216:219], v[172:175], v[88:91]
	v_mfma_f32_16x16x32_f16 v[76:79], v[208:211], v[180:183], v[76:79]
	v_mfma_f32_16x16x32_f16 v[72:75], v[216:219], v[180:183], v[72:75]
	s_mov_b32 m0, s49
	v_lshl_add_u64 v[246:247], s[24:25], 0, v[2:3]
	s_barrier
	ds_read_b128 v[152:155], v241 offset:16384
	ds_read_b128 v[156:159], v241 offset:17408
	ds_read_b128 v[160:163], v241 offset:18432
	ds_read_b128 v[164:167], v241 offset:19456
	ds_read_b128 v[168:171], v241 offset:20480
	ds_read_b128 v[172:175], v241 offset:21504
	ds_read_b128 v[176:179], v241 offset:22528
	ds_read_b128 v[180:183], v241 offset:23552
	global_load_lds_dwordx4 v[246:247], off
	v_lshl_add_u64 v[248:249], s[24:25], 0, v[196:197]
	s_mov_b32 m0, s51
	s_nop 0
	global_load_lds_dwordx4 v[248:249], off
	s_waitcnt lgkmcnt(4)
	s_barrier
	s_waitcnt lgkmcnt(0)
	v_mfma_f32_16x16x32_f16 v[68:71], v[136:139], v[152:155], v[68:71]
	v_mfma_f32_16x16x32_f16 v[64:67], v[144:147], v[152:155], v[64:67]
	v_mfma_f32_16x16x32_f16 v[52:55], v[136:139], v[160:163], v[52:55]
	v_mfma_f32_16x16x32_f16 v[48:51], v[144:147], v[160:163], v[48:51]
	v_mfma_f32_16x16x32_f16 v[36:39], v[136:139], v[168:171], v[36:39]
	v_mfma_f32_16x16x32_f16 v[32:35], v[144:147], v[168:171], v[32:35]
	v_mfma_f32_16x16x32_f16 v[20:23], v[136:139], v[176:179], v[20:23]
	v_mfma_f32_16x16x32_f16 v[16:19], v[144:147], v[176:179], v[16:19]
	v_mfma_f32_16x16x32_f16 v[68:71], v[140:143], v[156:159], v[68:71]
	v_mfma_f32_16x16x32_f16 v[64:67], v[148:151], v[156:159], v[64:67]
	v_mfma_f32_16x16x32_f16 v[52:55], v[140:143], v[164:167], v[52:55]
	v_mfma_f32_16x16x32_f16 v[48:51], v[148:151], v[164:167], v[48:51]
	v_mfma_f32_16x16x32_f16 v[36:39], v[140:143], v[172:175], v[36:39]
	v_mfma_f32_16x16x32_f16 v[32:35], v[148:151], v[172:175], v[32:35]
	v_mfma_f32_16x16x32_f16 v[20:23], v[140:143], v[180:183], v[20:23]
	v_mfma_f32_16x16x32_f16 v[16:19], v[148:151], v[180:183], v[16:19]
	s_barrier
; #define PG8_STAGE(bufoff, gbase, voff) do { _Pragma("unroll") for (int _i = 0; _i < 2; ++_i) \
;         __builtin_amdgcn_global_load_lds((const unsigned*)((const char*)(gbase) + (voff)[_i]), (LAS unsigned*)(lds + (bufoff) + ldsw + _i * 8192), 16, 0, 0); } while (0)
; #define PG8_LDA(dst, b, h) do { _Pragma("unroll") for (int m = 0; m < 4; ++m) _Pragma("unroll") for (int k = 0; k < 2; ++k) dst[m][k] = *(const LAS f16x8*)(lds + PG8_SA(b, h) + aoff + m * 2048 + k * 1024); } while (0)
; #define PG8_LDB(dst, b, h) do { _Pragma("unroll") for (int n = 0; n < 2; ++n) _Pragma("unroll") for (int k = 0; k < 2; ++k) dst[n][k] = *(const LAS f16x8*)(lds + PG8_SB(b, h) + boff + n * 2048 + k * 1024); } while (0)
; #define PG8_MMA(ai, bj, At, Bt) do { __builtin_amdgcn_s_setprio(1); _Pragma("unroll") for (int m = 0; m < 4; ++m) _Pragma("unroll") for (int n = 0; n < 2; ++n) _Pragma("unroll") for (int k = 0; k < 2; ++k) \
;         acc[ai][bj][m][n] = __builtin_amdgcn_mfma_f32_16x16x32_f16(Bt[n][k], At[m][k], acc[ai][bj][m][n], 0, 0, 0); __builtin_amdgcn_s_setprio(0); } while (0)
; #define PG8_WAIT_V(n) asm volatile("s_waitcnt vmcnt(" #n ")" ::: "memory")
; #define PG8_WAIT_L(n) asm volatile("s_waitcnt lgkmcnt(" #n ")" ::: "memory")
; #define PG8_BAR __builtin_amdgcn_s_barrier()
; #define PG8_SCHED __builtin_amdgcn_sched_barrier(0)
; __device__ __forceinline__ void gemm_phase(LAS unsigned char* lds, const Job& g, const pg8::StaticOrder& S) {
;     ...
;             PG8_STAGE(PG8_SB(0, 1), b2 + hB, voffB);
;             PG8_WAIT_V(6); PG8_BAR; PG8_MMA(1, 1, At, B1); PG8_BAR;
;             PG8_LDB(B0, 1, 0); PG8_SCHED; PG8_LDA(At, 1, 0); PG8_STAGE(PG8_SA(0, 1), a2 + hA, voffA);
;             PG8_WAIT_L(8); PG8_BAR; PG8_WAIT_L(0); PG8_MMA(0, 0, At, B0); PG8_BAR; PG8_SCHED;
;             PG8_LDB(B1, 1, 1); PG8_STAGE(PG8_SB(1, 0), b3, voffB);
;             PG8_BAR; PG8_WAIT_L(0); PG8_MMA(0, 1, At, B1); PG8_BAR;
;             PG8_LDA(At, 1, 1); PG8_STAGE(PG8_SA(1, 0), a3, voffA);
	s_add_u32 s62, s62, s90
	s_addc_u32 s63, s63, s91
	s_add_i32 s45, s45, s48
	v_lshl_add_u64 v[250:251], s[62:63], 0, v[194:195]
	s_mov_b32 m0, s45
	v_lshl_add_u64 v[252:253], s[62:63], 0, v[198:199]
	global_load_lds_dwordx4 v[250:251], off
	s_add_i32 m0, s45, 0x2000
	s_nop 0
	global_load_lds_dwordx4 v[252:253], off
	s_waitcnt vmcnt(6)
	s_barrier
	v_mfma_f32_16x16x32_f16 v[60:63], v[204:207], v[152:155], v[60:63]
	v_mfma_f32_16x16x32_f16 v[56:59], v[212:215], v[152:155], v[56:59]
	v_mfma_f32_16x16x32_f16 v[44:47], v[204:207], v[160:163], v[44:47]
	v_mfma_f32_16x16x32_f16 v[40:43], v[212:215], v[160:163], v[40:43]
	v_mfma_f32_16x16x32_f16 v[28:31], v[204:207], v[168:171], v[28:31]
	v_mfma_f32_16x16x32_f16 v[24:27], v[212:215], v[168:171], v[24:27]
	v_mfma_f32_16x16x32_f16 v[12:15], v[204:207], v[176:179], v[12:15]
	v_mfma_f32_16x16x32_f16 v[8:11], v[212:215], v[176:179], v[8:11]
	v_mfma_f32_16x16x32_f16 v[60:63], v[208:211], v[156:159], v[60:63]
	v_mfma_f32_16x16x32_f16 v[56:59], v[216:219], v[156:159], v[56:59]
	v_mfma_f32_16x16x32_f16 v[44:47], v[208:211], v[164:167], v[44:47]
	v_mfma_f32_16x16x32_f16 v[40:43], v[216:219], v[164:167], v[40:43]
	v_mfma_f32_16x16x32_f16 v[28:31], v[208:211], v[172:175], v[28:31]
	v_mfma_f32_16x16x32_f16 v[24:27], v[216:219], v[172:175], v[24:27]
	v_mfma_f32_16x16x32_f16 v[12:15], v[208:211], v[180:183], v[12:15]
	v_mfma_f32_16x16x32_f16 v[8:11], v[216:219], v[180:183], v[8:11]
	s_add_i32 s45, 0, 0x18000
	v_add_u32_e32 v148, s45, v238
	s_barrier
	ds_read_b128 v[136:139], v148
	ds_read_b128 v[140:143], v148 offset:1024
	ds_read_b128 v[144:147], v148 offset:2048
	ds_read_b128 v[148:151], v148 offset:3072
	s_add_u32 s24, s24, s36
	s_addc_u32 s25, s25, s37
	s_mov_b32 m0, s3
	v_lshl_add_u64 v[204:205], s[24:25], 0, v[2:3]
	ds_read_b128 v[152:155], v241 offset:32768
	ds_read_b128 v[156:159], v241 offset:33792
	ds_read_b128 v[160:163], v241 offset:34816
	ds_read_b128 v[164:167], v241 offset:35840
	ds_read_b128 v[168:171], v241 offset:36864
	ds_read_b128 v[172:175], v241 offset:37888
	ds_read_b128 v[176:179], v241 offset:38912
	ds_read_b128 v[180:183], v241 offset:39936
	global_load_lds_dwordx4 v[204:205], off
	v_lshl_add_u64 v[204:205], s[24:25], 0, v[196:197]
	s_mov_b32 m0, s99
	s_nop 0
	global_load_lds_dwordx4 v[204:205], off
	s_waitcnt lgkmcnt(8)
	s_barrier
	s_waitcnt lgkmcnt(0)
	v_mfma_f32_16x16x32_f16 v[132:135], v[136:139], v[152:155], v[132:135]
	v_mfma_f32_16x16x32_f16 v[128:131], v[144:147], v[152:155], v[128:131]
	v_mfma_f32_16x16x32_f16 v[116:119], v[136:139], v[160:163], v[116:119]
	v_mfma_f32_16x16x32_f16 v[112:115], v[144:147], v[160:163], v[112:115]
	v_mfma_f32_16x16x32_f16 v[100:103], v[136:139], v[168:171], v[100:103]
	v_mfma_f32_16x16x32_f16 v[96:99], v[144:147], v[168:171], v[96:99]
	v_mfma_f32_16x16x32_f16 v[84:87], v[136:139], v[176:179], v[84:87]
	v_mfma_f32_16x16x32_f16 v[80:83], v[144:147], v[176:179], v[80:83]
	v_mfma_f32_16x16x32_f16 v[132:135], v[140:143], v[156:159], v[132:135]
	v_mfma_f32_16x16x32_f16 v[128:131], v[148:151], v[156:159], v[128:131]
	v_mfma_f32_16x16x32_f16 v[116:119], v[140:143], v[164:167], v[116:119]
	v_mfma_f32_16x16x32_f16 v[112:115], v[148:151], v[164:167], v[112:115]
	v_mfma_f32_16x16x32_f16 v[100:103], v[140:143], v[172:175], v[100:103]
	v_mfma_f32_16x16x32_f16 v[96:99], v[148:151], v[172:175], v[96:99]
	v_mfma_f32_16x16x32_f16 v[84:87], v[140:143], v[180:183], v[84:87]
	v_mfma_f32_16x16x32_f16 v[80:83], v[148:151], v[180:183], v[80:83]
	s_barrier
	s_add_i32 s24, 0, 0x1c000
	s_add_i32 s25, s45, s48
	v_add_u32_e32 v216, s24, v238
	v_lshl_add_u64 v[242:243], v[242:243], 0, s[76:77]
	s_mov_b32 m0, s25
	ds_read_b128 v[204:207], v216
	ds_read_b128 v[208:211], v216 offset:1024
	ds_read_b128 v[212:215], v216 offset:2048
	ds_read_b128 v[216:219], v216 offset:3072
	global_load_lds_dwordx4 v[242:243], off
	v_lshl_add_u64 v[242:243], v[244:245], 0, s[76:77]
	s_add_i32 m0, s25, 0x2000
	s_nop 0
	global_load_lds_dwordx4 v[242:243], off
	s_barrier
	s_waitcnt lgkmcnt(0)
	v_mfma_f32_16x16x32_f16 v[124:127], v[204:207], v[152:155], v[124:127]
	v_mfma_f32_16x16x32_f16 v[120:123], v[212:215], v[152:155], v[120:123]
	v_mfma_f32_16x16x32_f16 v[108:111], v[204:207], v[160:163], v[108:111]
	v_mfma_f32_16x16x32_f16 v[104:107], v[212:215], v[160:163], v[104:107]
	v_mfma_f32_16x16x32_f16 v[92:95], v[204:207], v[168:171], v[92:95]
	v_mfma_f32_16x16x32_f16 v[88:91], v[212:215], v[168:171], v[88:91]
	v_mfma_f32_16x16x32_f16 v[76:79], v[204:207], v[176:179], v[76:79]
	v_mfma_f32_16x16x32_f16 v[72:75], v[212:215], v[176:179], v[72:75]
	v_mfma_f32_16x16x32_f16 v[124:127], v[208:211], v[156:159], v[124:127]
	v_mfma_f32_16x16x32_f16 v[120:123], v[216:219], v[156:159], v[120:123]
	v_mfma_f32_16x16x32_f16 v[108:111], v[208:211], v[164:167], v[108:111]
	v_mfma_f32_16x16x32_f16 v[104:107], v[216:219], v[164:167], v[104:107]
	v_mfma_f32_16x16x32_f16 v[92:95], v[208:211], v[172:175], v[92:95]
	v_mfma_f32_16x16x32_f16 v[88:91], v[216:219], v[172:175], v[88:91]
	v_mfma_f32_16x16x32_f16 v[76:79], v[208:211], v[180:183], v[76:79]
	v_mfma_f32_16x16x32_f16 v[72:75], v[216:219], v[180:183], v[72:75]
	s_mov_b32 m0, s87
	v_lshl_add_u64 v[242:243], v[246:247], 0, s[76:77]
	s_barrier
	ds_read_b128 v[152:155], v241 offset:49152
	ds_read_b128 v[156:159], v241 offset:50176
	ds_read_b128 v[160:163], v241 offset:51200
	ds_read_b128 v[164:167], v241 offset:52224
	ds_read_b128 v[168:171], v241 offset:53248
	ds_read_b128 v[172:175], v241 offset:54272
	ds_read_b128 v[176:179], v241 offset:55296
	ds_read_b128 v[180:183], v241 offset:56320
	global_load_lds_dwordx4 v[242:243], off
	v_lshl_add_u64 v[242:243], v[248:249], 0, s[76:77]
	s_mov_b32 m0, s96
	s_nop 0
	global_load_lds_dwordx4 v[242:243], off
	s_waitcnt lgkmcnt(4)
	s_barrier
; #define PG8_STAGE(bufoff, gbase, voff) do { _Pragma("unroll") for (int _i = 0; _i < 2; ++_i) \
;         __builtin_amdgcn_global_load_lds((const unsigned*)((const char*)(gbase) + (voff)[_i]), (LAS unsigned*)(lds + (bufoff) + ldsw + _i * 8192), 16, 0, 0); } while (0)
; #define PG8_MMA(ai, bj, At, Bt) do { __builtin_amdgcn_s_setprio(1); _Pragma("unroll") for (int m = 0; m < 4; ++m) _Pragma("unroll") for (int n = 0; n < 2; ++n) _Pragma("unroll") for (int k = 0; k < 2; ++k) \
;         acc[ai][bj][m][n] = __builtin_amdgcn_mfma_f32_16x16x32_f16(Bt[n][k], At[m][k], acc[ai][bj][m][n], 0, 0, 0); __builtin_amdgcn_s_setprio(0); } while (0)
; #define PG8_WAIT_V(n) asm volatile("s_waitcnt vmcnt(" #n ")" ::: "memory")
; #define PG8_WAIT_L(n) asm volatile("s_waitcnt lgkmcnt(" #n ")" ::: "memory")
; #define PG8_BAR __builtin_amdgcn_s_barrier()
; #define PG8_SCHED __builtin_amdgcn_sched_barrier(0)
; __device__ __forceinline__ void epilogue(const Job& J, const f32x4 (&acc)[2][2][4][2], const pg8::Unit& u, int wr, int wc, int fr, int fq) {
;     ...
;     } else {
;         const int colg = u.pn * 256 + ct;
;         f32x4 bs[2][2];
; #pragma unroll
;         for (int bj = 0; bj < 2; ++bj) { bs[bj][0] = *(const f32x4*)(J.f0 + colg + bj * 128); bs[bj][1] = *(const f32x4*)(J.f0 + colg + bj * 128 + 4); }
; #pragma unroll
;         for (int ai = 0; ai < 2; ++ai)
; #pragma unroll
;             for (int mh = 0; mh < 2; ++mh) {
;                 f16x8 pl[2][2], xm[2][2];
; #pragma unroll
;                 for (int mm = 0; mm < 2; ++mm)
; #pragma unroll
;                     for (int bj = 0; bj < 2; ++bj) { const size_t o = (size_t)(row0 + ai * 128 + (mh * 2 + mm) * 16) * 2048 + colg + bj * 128;
;                         pl[mm][bj] = *(const f16x8*)(J.h0 + o); xm[mm][bj] = *(const f16x8*)(J.h1 + o); }
; __device__ __forceinline__ void gemm_phase(LAS unsigned char* lds, const Job& g, const pg8::StaticOrder& S) {
;     ...
;             PG8_BAR; PG8_WAIT_L(0); PG8_MMA(1, 0, At, B0); PG8_BAR; PG8_SCHED;
;             PG8_STAGE(PG8_SB(1, 1), b3 + hB, voffB);
;             PG8_WAIT_V(6); PG8_BAR; PG8_MMA(1, 1, At, B1); PG8_BAR;
	s_waitcnt lgkmcnt(0)
	v_mfma_f32_16x16x32_f16 v[68:71], v[136:139], v[152:155], v[68:71]
	v_mfma_f32_16x16x32_f16 v[64:67], v[144:147], v[152:155], v[64:67]
	v_mfma_f32_16x16x32_f16 v[52:55], v[136:139], v[160:163], v[52:55]
	v_mfma_f32_16x16x32_f16 v[48:51], v[144:147], v[160:163], v[48:51]
	v_mfma_f32_16x16x32_f16 v[36:39], v[136:139], v[168:171], v[36:39]
	v_mfma_f32_16x16x32_f16 v[32:35], v[144:147], v[168:171], v[32:35]
	v_mfma_f32_16x16x32_f16 v[20:23], v[136:139], v[176:179], v[20:23]
	v_mfma_f32_16x16x32_f16 v[16:19], v[144:147], v[176:179], v[16:19]
	v_mfma_f32_16x16x32_f16 v[68:71], v[140:143], v[156:159], v[68:71]
	v_mfma_f32_16x16x32_f16 v[64:67], v[148:151], v[156:159], v[64:67]
	v_mfma_f32_16x16x32_f16 v[52:55], v[140:143], v[164:167], v[52:55]
	v_mfma_f32_16x16x32_f16 v[48:51], v[148:151], v[164:167], v[48:51]
	v_mfma_f32_16x16x32_f16 v[36:39], v[140:143], v[172:175], v[36:39]
	v_mfma_f32_16x16x32_f16 v[32:35], v[148:151], v[172:175], v[32:35]
	v_mfma_f32_16x16x32_f16 v[20:23], v[140:143], v[180:183], v[20:23]
	v_mfma_f32_16x16x32_f16 v[16:19], v[148:151], v[180:183], v[16:19]
	s_barrier
	s_add_i32 s24, s24, s48
	v_lshl_add_u64 v[136:137], v[250:251], 0, s[76:77]
	s_mov_b32 m0, s24
	s_nop 0
	global_load_lds_dwordx4 v[136:137], off
	v_lshl_add_u64 v[136:137], v[252:253], 0, s[76:77]
	s_add_i32 m0, s24, 0x2000
	s_nop 0
	global_load_lds_dwordx4 v[136:137], off
	s_waitcnt vmcnt(6)
	s_barrier
	v_mfma_f32_16x16x32_f16 v[60:63], v[204:207], v[152:155], v[60:63]
	v_mfma_f32_16x16x32_f16 v[56:59], v[212:215], v[152:155], v[56:59]
	v_mfma_f32_16x16x32_f16 v[44:47], v[204:207], v[160:163], v[44:47]
	v_mfma_f32_16x16x32_f16 v[40:43], v[212:215], v[160:163], v[40:43]
	v_mfma_f32_16x16x32_f16 v[28:31], v[204:207], v[168:171], v[28:31]
	v_mfma_f32_16x16x32_f16 v[24:27], v[212:215], v[168:171], v[24:27]
	v_mfma_f32_16x16x32_f16 v[12:15], v[204:207], v[176:179], v[12:15]
	v_mfma_f32_16x16x32_f16 v[8:11], v[212:215], v[176:179], v[8:11]
	v_mfma_f32_16x16x32_f16 v[60:63], v[208:211], v[156:159], v[60:63]
	v_mfma_f32_16x16x32_f16 v[56:59], v[216:219], v[156:159], v[56:59]
	v_mfma_f32_16x16x32_f16 v[44:47], v[208:211], v[164:167], v[44:47]
	v_mfma_f32_16x16x32_f16 v[40:43], v[216:219], v[164:167], v[40:43]
	v_mfma_f32_16x16x32_f16 v[28:31], v[208:211], v[172:175], v[28:31]
	v_mfma_f32_16x16x32_f16 v[24:27], v[216:219], v[172:175], v[24:27]
	v_mfma_f32_16x16x32_f16 v[12:15], v[208:211], v[180:183], v[12:15]
	v_mfma_f32_16x16x32_f16 v[8:11], v[216:219], v[180:183], v[8:11]
	s_add_u32 s10, s10, 0x100
	s_addc_u32 s11, s11, 0
	s_add_u32 vcc_lo, vcc_lo, 0x100
	s_addc_u32 vcc_hi, vcc_hi, 0
	s_cmp_ge_u32 s44, s98
	s_mov_b32 s24, s44
	s_barrier
	s_cbranch_scc0 .LBB0_182
	v_lshl_add_u32 v204, s19, 8, v1
	s_cmp_lt_i32 s21, 2
	s_mov_b64 s[10:11], -1
	s_cbranch_scc1 .LBB0_205
	s_cmp_gt_i32 s21, 2
	s_cbranch_scc0 .LBB0_202
	v_lshl_or_b32 v206, s58, 8, v239
	v_ashrrev_i32_e32 v207, 31, v206
	v_lshl_add_u64 v[140:141], v[206:207], 2, s[56:57]
	global_load_dwordx4 v[144:147], v[140:141], off offset:16
	global_load_dwordx4 v[148:151], v[140:141], off
	global_load_dwordx4 v[136:139], v[140:141], off offset:528
	s_nop 0
	global_load_dwordx4 v[140:143], v[140:141], off offset:512
	v_and_b32_e32 v153, 64, v236
	v_xor_b32_e32 v152, 16, v236
	v_add_u32_e32 v153, 64, v153
	v_cmp_lt_i32_e32 vcc, v152, v153
	v_ashrrev_i32_e32 v205, 31, v204
	s_waitcnt vmcnt(0)
	v_add_f32_e32 v212, v132, v148
	v_cndmask_b32_e32 v152, v236, v152, vcc
	v_lshlrev_b32_e32 v243, 2, v152
	v_xor_b32_e32 v152, 32, v236
	v_cmp_lt_i32_e32 vcc, v152, v153
	v_mul_f32_e32 v212, 0xbfb8aa3b, v212
	v_exp_f32_e32 v212, v212
	v_cndmask_b32_e32 v152, v236, v152, vcc
	v_lshlrev_b32_e32 v242, 2, v152
	v_lshlrev_b64 v[152:153], 11, v[204:205]
	v_lshl_add_u64 v[152:153], v[152:153], 0, v[206:207]
	v_lshlrev_b64 v[210:211], 1, v[152:153]
	v_lshl_add_u64 v[152:153], s[66:67], 0, v[210:211]
	global_load_dwordx4 v[176:179], v[152:153], off
	v_lshl_add_u64 v[154:155], s[42:43], 0, v[210:211]
	global_load_dwordx4 v[180:183], v[154:155], off
	global_load_dwordx4 v[168:171], v[152:153], off offset:256
	global_load_dwordx4 v[172:175], v[154:155], off offset:256
	v_add_f32_e32 v212, 1.0, v212
	v_rcp_f32_e32 v218, v212
	v_add_f32_e32 v212, v128, v144
	v_mul_f32_e32 v212, 0xbfb8aa3b, v212
	v_exp_f32_e32 v212, v212
	v_or_b32_e32 v152, 16, v204
	v_ashrrev_i32_e32 v153, 31, v152
	v_lshlrev_b64 v[152:153], 11, v[152:153]
	v_lshl_add_u64 v[208:209], v[152:153], 0, v[206:207]
	v_add_f32_e32 v212, 1.0, v212
	v_lshlrev_b64 v[152:153], 1, v[208:209]
	v_rcp_f32_e32 v214, v212
	v_add_f32_e32 v212, v133, v149
	v_lshl_add_u64 v[154:155], s[66:67], 0, v[152:153]
	v_lshl_add_u64 v[156:157], s[42:43], 0, v[152:153]
	v_mul_f32_e32 v212, 0xbfb8aa3b, v212
	global_load_dwordx4 v[160:163], v[154:155], off
	global_load_dwordx4 v[164:167], v[156:157], off
	s_nop 0
	global_load_dwordx4 v[152:155], v[154:155], off offset:256
	s_nop 0
	global_load_dwordx4 v[156:159], v[156:157], off offset:256
	v_exp_f32_e32 v212, v212
	v_add_f32_e32 v213, v135, v151
	v_mul_f32_e32 v213, 0xbfb8aa3b, v213
	v_exp_f32_e32 v213, v213
	v_add_f32_e32 v212, 1.0, v212
	v_rcp_f32_e32 v219, v212
	v_add_f32_e32 v212, v129, v145
	v_mul_f32_e32 v212, 0xbfb8aa3b, v212
	v_exp_f32_e32 v212, v212
	v_add_f32_e32 v213, 1.0, v213
	v_rcp_f32_e32 v217, v213
	v_add_f32_e32 v213, v131, v147
	v_add_f32_e32 v212, 1.0, v212
	v_rcp_f32_e32 v215, v212
	v_add_f32_e32 v212, v134, v150
	v_mul_f32_e32 v212, 0xbfb8aa3b, v212
	v_exp_f32_e32 v212, v212
	v_mul_f32_e32 v213, 0xbfb8aa3b, v213
	v_exp_f32_e32 v213, v213
	v_lshl_add_u64 v[210:211], s[34:35], 0, v[210:211]
	v_add_f32_e32 v212, 1.0, v212
	v_rcp_f32_e32 v216, v212
	v_add_f32_e32 v212, v130, v146
	v_mul_f32_e32 v212, 0xbfb8aa3b, v212
	v_exp_f32_e32 v212, v212
	v_add_f32_e32 v213, 1.0, v213
	v_rcp_f32_e32 v213, v213
	v_add_f32_e32 v212, 1.0, v212
	v_rcp_f32_e32 v212, v212
	s_waitcnt vmcnt(0)
; __device__ __forceinline__ void st8acc(f16* p, const f32x4& v0, const f32x4& v1) { u32x4 w; w.x = pkh(v0[0], v0[1]); w.y = pkh(v0[2], v0[3]); w.z = pkh(v1[0], v1[1]); w.w = pkh(v1[2], v1[3]); *(u32x4*)p = w; }
; __device__ __forceinline__ float sigm(float x) { return __builtin_amdgcn_rcpf(1.0f + __expf(-x)); }
; __device__ __forceinline__ void epilogue(const Job& J, const f32x4 (&acc)[2][2][4][2], const pg8::Unit& u, int wr, int wc, int fr, int fq) {
;     ...
;                 for (int mm = 0; mm < 2; ++mm) {
;                     const int m = mh * 2 + mm, row = row0 + ai * 128 + m * 16; float q = 0.f;
; #pragma unroll
;                     for (int bj = 0; bj < 2; ++bj) { const size_t o = (size_t)row * 2048 + colg + bj * 128;
;                         f32x4 x0, x1;
;                         const f32x4 a0 = acc[ai][bj][m][0] + bs[bj][0], a1 = acc[ai][bj][m][1] + bs[bj][1];
; #pragma unroll
;                         for (int j = 0; j < 4; ++j) { x0[j] = (float)xm[mm][bj][j] + sigm(a0[j]) * (float)pl[mm][bj][j]; x1[j] = (float)xm[mm][bj][4 + j] + sigm(a1[j]) * (float)pl[mm][bj][4 + j]; }
;                         if (J.o32) { *(f32x4*)(J.o32 + o) = x0; *(f32x4*)(J.o32 + o + 4) = x1; } else st8acc(J.o16 + o, x0, x1);
;                         q += ((x0[0] * x0[0] + x0[1] * x0[1]) + (x0[2] * x0[2] + x0[3] * x0[3])) + ((x1[0] * x1[0] + x1[1] * x1[1]) + (x1[2] * x1[2] + x1[3] * x1[3])); }
;                     q += __shfl_xor(q, 16); q += __shfl_xor(q, 32);
;                     if (fq == 0) atomicAdd(J.xsq + row, q);
	v_cvt_f32_f16_e32 v244, v180
	v_cvt_f32_f16_sdwa v245, v180 dst_sel:DWORD dst_unused:UNUSED_PAD src0_sel:WORD_1
	v_cvt_f32_f16_e32 v246, v176
	v_cvt_f32_f16_sdwa v247, v176 dst_sel:DWORD dst_unused:UNUSED_PAD src0_sel:WORD_1
	v_cvt_f32_f16_e32 v180, v181
	v_cvt_f32_f16_sdwa v181, v181 dst_sel:DWORD dst_unused:UNUSED_PAD src0_sel:WORD_1
	v_pk_fma_f32 v[218:219], v[218:219], v[246:247], v[244:245]
	v_cvt_f32_f16_e32 v244, v177
	v_cvt_f32_f16_sdwa v245, v177 dst_sel:DWORD dst_unused:UNUSED_PAD src0_sel:WORD_1
	v_cvt_pk_f16_f32 v176, v218, v219
	v_cvt_f32_f16_e32 v246, v168
	v_cvt_f32_f16_sdwa v247, v168 dst_sel:DWORD dst_unused:UNUSED_PAD src0_sel:WORD_1
	v_pk_fma_f32 v[180:181], v[216:217], v[244:245], v[180:181]
	v_cvt_f32_f16_e32 v216, v182
	v_cvt_f32_f16_sdwa v217, v182 dst_sel:DWORD dst_unused:UNUSED_PAD src0_sel:WORD_1
	v_cvt_f32_f16_e32 v244, v178
	v_cvt_f32_f16_sdwa v245, v178 dst_sel:DWORD dst_unused:UNUSED_PAD src0_sel:WORD_1
	v_cvt_f32_f16_e32 v182, v183
	v_cvt_f32_f16_sdwa v183, v183 dst_sel:DWORD dst_unused:UNUSED_PAD src0_sel:WORD_1
	v_cvt_pk_f16_f32 v177, v180, v181
	v_pk_fma_f32 v[214:215], v[214:215], v[244:245], v[216:217]
	v_cvt_f32_f16_e32 v216, v179
	v_cvt_f32_f16_sdwa v217, v179 dst_sel:DWORD dst_unused:UNUSED_PAD src0_sel:WORD_1
	v_cvt_pk_f16_f32 v178, v214, v215
	v_cvt_f32_f16_e32 v244, v172
	v_cvt_f32_f16_sdwa v245, v172 dst_sel:DWORD dst_unused:UNUSED_PAD src0_sel:WORD_1
	v_pk_fma_f32 v[182:183], v[212:213], v[216:217], v[182:183]
	v_add_f32_e32 v213, v120, v136
	v_mul_f32_e32 v213, 0xbfb8aa3b, v213
	v_exp_f32_e32 v213, v213
	v_add_f32_e32 v217, v122, v138
	v_mul_f32_e32 v217, 0xbfb8aa3b, v217
	v_cvt_pk_f16_f32 v179, v182, v183
	v_add_f32_e32 v213, 1.0, v213
	v_exp_f32_e32 v217, v217
	global_store_dwordx4 v[210:211], v[176:179], off
	v_add_f32_e32 v212, v124, v140
	v_mul_f32_e32 v212, 0xbfb8aa3b, v212
	v_pk_mul_f32 v[178:179], v[180:181], v[180:181]
	v_pk_mul_f32 v[180:181], v[214:215], v[214:215]
	v_rcp_f32_e32 v214, v213
	v_add_f32_e32 v213, v125, v141
	v_mul_f32_e32 v213, 0xbfb8aa3b, v213
	v_exp_f32_e32 v212, v212
	v_exp_f32_e32 v213, v213
	v_add_f32_e32 v217, 1.0, v217
	v_pk_mul_f32 v[176:177], v[218:219], v[218:219]
	v_add_f32_e32 v216, v126, v142
	v_rcp_f32_e32 v218, v217
	v_add_f32_e32 v217, v127, v143
	v_mul_f32_e32 v216, 0xbfb8aa3b, v216
	v_mul_f32_e32 v217, 0xbfb8aa3b, v217
	v_add_f32_e32 v212, 1.0, v212
	v_add_f32_e32 v213, 1.0, v213
	v_exp_f32_e32 v216, v216
	v_exp_f32_e32 v217, v217
	v_rcp_f32_e32 v212, v212
	v_rcp_f32_e32 v213, v213
	v_add_f32_e32 v215, v121, v137
	v_mul_f32_e32 v215, 0xbfb8aa3b, v215
	v_exp_f32_e32 v215, v215
	v_add_f32_e32 v216, 1.0, v216
	v_add_f32_e32 v217, 1.0, v217
	v_rcp_f32_e32 v216, v216
	v_rcp_f32_e32 v217, v217
	v_pk_fma_f32 v[212:213], v[212:213], v[246:247], v[244:245]
	v_cvt_f32_f16_e32 v172, v173
	v_cvt_f32_f16_sdwa v173, v173 dst_sel:DWORD dst_unused:UNUSED_PAD src0_sel:WORD_1
	v_cvt_f32_f16_e32 v244, v169
	v_cvt_f32_f16_sdwa v245, v169 dst_sel:DWORD dst_unused:UNUSED_PAD src0_sel:WORD_1
	v_add_f32_e32 v219, v123, v139
	v_mul_f32_e32 v219, 0xbfb8aa3b, v219
	v_add_f32_e32 v215, 1.0, v215
	v_exp_f32_e32 v219, v219
	v_rcp_f32_e32 v215, v215
	v_pk_fma_f32 v[172:173], v[216:217], v[244:245], v[172:173]
	v_cvt_f32_f16_e32 v216, v174
	v_cvt_f32_f16_sdwa v217, v174 dst_sel:DWORD dst_unused:UNUSED_PAD src0_sel:WORD_1
	v_cvt_f32_f16_e32 v244, v170
	v_cvt_f32_f16_sdwa v245, v170 dst_sel:DWORD dst_unused:UNUSED_PAD src0_sel:WORD_1
	v_add_f32_e32 v219, 1.0, v219
	v_rcp_f32_e32 v219, v219
	v_cvt_f32_f16_e32 v174, v175
	v_pk_fma_f32 v[214:215], v[214:215], v[244:245], v[216:217]
	v_cvt_f32_f16_sdwa v175, v175 dst_sel:DWORD dst_unused:UNUSED_PAD src0_sel:WORD_1
	v_cvt_f32_f16_e32 v216, v171
	v_cvt_f32_f16_sdwa v217, v171 dst_sel:DWORD dst_unused:UNUSED_PAD src0_sel:WORD_1
	v_cvt_pk_f16_f32 v168, v212, v213
	v_cvt_pk_f16_f32 v169, v172, v173
	v_cvt_pk_f16_f32 v170, v214, v215
	v_pk_fma_f32 v[174:175], v[218:219], v[216:217], v[174:175]
	v_pk_mul_f32 v[182:183], v[182:183], v[182:183]
	v_cvt_pk_f16_f32 v171, v174, v175
	global_store_dwordx4 v[210:211], v[168:171], off offset:256
	v_pk_mul_f32 v[174:175], v[174:175], v[174:175]
	s_nop 0
	v_pk_mul_f32 v[168:169], v[212:213], v[212:213]
	v_pk_mul_f32 v[170:171], v[172:173], v[172:173]
	v_add_f32_e32 v168, v168, v169
	v_add_f32_e32 v170, v170, v171
	v_pk_mul_f32 v[172:173], v[214:215], v[214:215]
	v_add_f32_e32 v168, v168, v170
	v_add_f32_e32 v169, v182, v183
	v_add_f32_e32 v170, v180, v181
	v_add_f32_e32 v174, v174, v175
	v_add_f32_e32 v172, v172, v173
	v_add_f32_e32 v169, v170, v169
	v_add_f32_e32 v170, v178, v179
	v_add_f32_e32 v171, v176, v177
	v_add_f32_e32 v172, v172, v174
	v_add_f32_e32 v170, v171, v170
	v_add_f32_e32 v168, v168, v172
	v_add_f32_e32 v169, v170, v169
	v_add_f32_e32 v168, v169, v168
	ds_bpermute_b32 v169, v243, v168
	v_lshl_add_u64 v[180:181], v[204:205], 2, s[60:61]
	s_waitcnt lgkmcnt(0)
	v_add_f32_e32 v168, v168, v169
	ds_bpermute_b32 v169, v242, v168
	s_and_saveexec_b64 s[10:11], s[4:5]
	s_cbranch_execz .LBB0_187
	s_waitcnt lgkmcnt(0)
	v_add_f32_e32 v168, v168, v169
	global_atomic_add_f32 v[180:181], v168, off
